# plus hand-written context-row LayerNorm (all loads issued up front, one wait) at both LN sites
# speedup vs baseline: 1.0059x; 1.0059x over previous
; #define IDS() int tid_ = threadIdx.x; asm volatile("" : "+v"(tid_)); const int lane_ = tid_ & 63, wave_ = __builtin_amdgcn_readfirstlane(tid_ >> 6); const int gw_ = vcu * NWAVES + wave_; (void)lane_; (void)gw_
; __device__ __forceinline__ void ln_rows_ctx(float* xC, const float* xCin, const float* g, const float* b, const float* modp, bf16* U, int gw, int ngw, int lane, const float* part, const float* gate8, int nsplit) {
;     for (int r = gw; r < MC; r += ngw) {
;         f32x4 v[4]; float s = 0.f;
; #pragma unroll
;         for (int j = 0; j < 4; ++j) { const int col = 4 * (lane + 64 * j); v[j] = *(const f32x4*)(xCin + (size_t)r * DM + col);
;             if (part) { const bf16* pp = (const bf16*)part + (size_t)r * DM + col; f32x4 ps = {0.f, 0.f, 0.f, 0.f};
;                 for (int k = 0; k < nsplit; ++k) { const v2u w = *(const v2u*)(pp + (size_t)k * 2048 * 1024); ps = ps + (f32x4){bflo(w.x), bfhi(w.x), bflo(w.y), bfhi(w.y)}; }
; __global__ void __launch_bounds__(NTHR, 2) trunk_fwd(Args a) {
;     ...
;         { IDS(); ln_rows(a.out, XC, mrows, a.ln1_g + l * DM, a.ln1_b + l * DM, modl + 3 * 1024, U, gw_, ngw, lane_, nullptr, need_ctx ? RETC : nullptr, modl + 2 * 1024 + 8 * 6144, l == 0 ? a.ctx : nullptr, U, (bf16*)a.out); }
.LBB0_1274:
	v_readlane_b32 s0, v253, 45
	v_readlane_b32 s1, v253, 46
	v_readlane_b32 s4, v255, 3
	s_andn2_b64 vcc, exec, s[0:1]
	v_cndmask_b32_e64 v0, 0, 1, s[0:1]
	v_cmp_ne_u32_e64 s[82:83], 1, v0
	v_readlane_b32 s5, v255, 4
	v_readlane_b32 s6, v254, 33
	s_cbranch_vccnz .LBB0_1279
	s_cmpk_gt_i32 s48, 0x7ff
	s_cbranch_scc1 .LBB0_1279
	v_readlane_b32 s26, v253, 41
	s_mov_b32 s7, s48
	s_mov_b64 s[10:11], s[18:19]
	s_mov_b64 s[14:15], s[20:21]
	s_nop 1
	s_mul_i32 s27, s26, 0x36000
	s_add_u32 s28, s94, 0x5a00000
	s_addc_u32 s29, s95, 0
	s_add_u32 s28, s28, s27
	s_addc_u32 s29, s29, 0
	s_add_u32 s8, s28, 0x32000
	s_addc_u32 s9, s29, 0
	s_add_u32 s20, s28, 0x33000
	s_addc_u32 s21, s29, 0
	s_add_u32 s2, s94, 0x6800000
	s_addc_u32 s3, s95, 0
	s_add_u32 s24, s94, 0x6000000
	s_addc_u32 s25, s95, 0
	s_add_u32 s22, s64, 0x4000000
	s_addc_u32 s23, s65, 0
	v_readlane_b32 s0, v252, 12
	v_readlane_b32 s1, v252, 13
	s_nop 3
	s_cmp_eq_u32 s26, 0
	s_cselect_b32 s0, s0, s24
	s_cselect_b32 s1, s1, s25
	s_mov_b32 s13, 4
	s_mov_b32 s19, 0
.Lctxx_entry:
	v_mbcnt_lo_u32_b32 v2, -1, 0
	v_mbcnt_hi_u32_b32 v2, -1, v2
	s_lshl_b32 s26, s7, 12
	s_lshl_b32 s27, s7, 11
	v_lshlrev_b32_e32 v3, 4, v2
	v_lshlrev_b32_e32 v4, 3, v2
	s_add_u32 s0, s0, s26
	s_addc_u32 s1, s1, 0
	s_add_u32 s24, s24, s26
	s_addc_u32 s25, s25, 0
	s_add_u32 s2, s2, s27
	s_addc_u32 s3, s3, 0
	s_add_u32 s22, s22, s27
	s_addc_u32 s23, s23, 0
	s_add_u32 s28, s20, 0x1000
	s_addc_u32 s29, s21, 0
	global_load_dwordx4 v[8:11], v3, s[0:1]
	global_load_dwordx4 v[12:15], v3, s[0:1] offset:1024
	global_load_dwordx4 v[16:19], v3, s[0:1] offset:2048
	global_load_dwordx4 v[20:23], v3, s[0:1] offset:3072
	global_load_dwordx2 v[130:131], v4, s[2:3]
	global_load_dwordx2 v[132:133], v4, s[2:3] offset:512
	global_load_dwordx2 v[134:135], v4, s[2:3] offset:1024
	global_load_dwordx2 v[136:137], v4, s[2:3] offset:1536
	s_add_u32 s2, s2, 0x400000
	s_addc_u32 s3, s3, 0
	global_load_dwordx2 v[138:139], v4, s[2:3]
	global_load_dwordx2 v[140:141], v4, s[2:3] offset:512
	global_load_dwordx2 v[142:143], v4, s[2:3] offset:1024
	global_load_dwordx2 v[144:145], v4, s[2:3] offset:1536
	s_add_u32 s2, s2, 0x400000
	s_addc_u32 s3, s3, 0
	global_load_dwordx2 v[146:147], v4, s[2:3]
	global_load_dwordx2 v[148:149], v4, s[2:3] offset:512
	global_load_dwordx2 v[150:151], v4, s[2:3] offset:1024
	global_load_dwordx2 v[152:153], v4, s[2:3] offset:1536
	s_add_u32 s2, s2, 0x400000
	s_addc_u32 s3, s3, 0
	global_load_dwordx2 v[154:155], v4, s[2:3]
	global_load_dwordx2 v[156:157], v4, s[2:3] offset:512
	global_load_dwordx2 v[158:159], v4, s[2:3] offset:1024
	global_load_dwordx2 v[160:161], v4, s[2:3] offset:1536
	s_add_u32 s2, s2, 0x400000
	s_addc_u32 s3, s3, 0
	s_cmp_eq_u32 s13, 8
	s_cbranch_scc0 .Lctxx_ld_done
	global_load_dwordx2 v[162:163], v4, s[2:3]
	global_load_dwordx2 v[164:165], v4, s[2:3] offset:512
	global_load_dwordx2 v[166:167], v4, s[2:3] offset:1024
	global_load_dwordx2 v[168:169], v4, s[2:3] offset:1536
	s_add_u32 s2, s2, 0x400000
	s_addc_u32 s3, s3, 0
	global_load_dwordx2 v[170:171], v4, s[2:3]
	global_load_dwordx2 v[172:173], v4, s[2:3] offset:512
	global_load_dwordx2 v[174:175], v4, s[2:3] offset:1024
	global_load_dwordx2 v[176:177], v4, s[2:3] offset:1536
	s_add_u32 s2, s2, 0x400000
	s_addc_u32 s3, s3, 0
	global_load_dwordx2 v[178:179], v4, s[2:3]
	global_load_dwordx2 v[180:181], v4, s[2:3] offset:512
	global_load_dwordx2 v[182:183], v4, s[2:3] offset:1024
	global_load_dwordx2 v[184:185], v4, s[2:3] offset:1536
	s_add_u32 s2, s2, 0x400000
	s_addc_u32 s3, s3, 0
	global_load_dwordx2 v[186:187], v4, s[2:3]
	global_load_dwordx2 v[188:189], v4, s[2:3] offset:512
	global_load_dwordx2 v[190:191], v4, s[2:3] offset:1024
	global_load_dwordx2 v[192:193], v4, s[2:3] offset:1536
.Lctxx_ld_done:
	global_load_dwordx4 v[24:27], v3, s[8:9]
	global_load_dwordx4 v[28:31], v3, s[8:9] offset:1024
	global_load_dwordx4 v[32:35], v3, s[8:9] offset:2048
	global_load_dwordx4 v[36:39], v3, s[8:9] offset:3072
	global_load_dwordx4 v[40:43], v3, s[10:11]
	global_load_dwordx4 v[44:47], v3, s[10:11] offset:1024
	global_load_dwordx4 v[48:51], v3, s[10:11] offset:2048
	global_load_dwordx4 v[52:55], v3, s[10:11] offset:3072
	global_load_dwordx4 v[56:59], v3, s[14:15]
	global_load_dwordx4 v[60:63], v3, s[14:15] offset:1024
	global_load_dwordx4 v[64:67], v3, s[14:15] offset:2048
	global_load_dwordx4 v[68:71], v3, s[14:15] offset:3072
	global_load_dwordx4 v[86:89], v3, s[20:21]
	global_load_dwordx4 v[90:93], v3, s[20:21] offset:1024
	global_load_dwordx4 v[94:97], v3, s[20:21] offset:2048
	global_load_dwordx4 v[98:101], v3, s[20:21] offset:3072
	global_load_dwordx4 v[226:229], v3, s[28:29]
	global_load_dwordx4 v[230:233], v3, s[28:29] offset:1024
	global_load_dwordx4 v[234:237], v3, s[28:29] offset:2048
	global_load_dwordx4 v[238:241], v3, s[28:29] offset:3072
	s_waitcnt vmcnt(0)
; __device__ __forceinline__ void ln_rows_ctx(float* xC, const float* xCin, const float* g, const float* b, const float* modp, bf16* U, int gw, int ngw, int lane, const float* part, const float* gate8, int nsplit) {
;     ...
;             if (part) { const bf16* pp = (const bf16*)part + (size_t)r * DM + col; f32x4 ps = {0.f, 0.f, 0.f, 0.f};
;                 for (int k = 0; k < nsplit; ++k) { const v2u w = *(const v2u*)(pp + (size_t)k * 2048 * 1024); ps = ps + (f32x4){bflo(w.x), bfhi(w.x), bflo(w.y), bfhi(w.y)}; }
;                 v[j] = v[j] * ALPHA + *(const f32x4*)(gate8 + col) * ps; }
	v_lshlrev_b32_e32 v102, 16, v130
	v_and_b32_e32 v103, 0xffff0000, v130
	v_lshlrev_b32_e32 v104, 16, v131
	v_and_b32_e32 v105, 0xffff0000, v131
	v_lshlrev_b32_e32 v106, 16, v132
	v_and_b32_e32 v107, 0xffff0000, v132
	v_lshlrev_b32_e32 v108, 16, v133
	v_and_b32_e32 v109, 0xffff0000, v133
	v_lshlrev_b32_e32 v110, 16, v134
	v_and_b32_e32 v111, 0xffff0000, v134
	v_lshlrev_b32_e32 v112, 16, v135
	v_and_b32_e32 v113, 0xffff0000, v135
	v_lshlrev_b32_e32 v194, 16, v136
	v_and_b32_e32 v195, 0xffff0000, v136
	v_lshlrev_b32_e32 v196, 16, v137
	v_and_b32_e32 v197, 0xffff0000, v137
	v_lshlrev_b32_e32 v74, 16, v138
	v_and_b32_e32 v75, 0xffff0000, v138
	v_add_f32_e32 v102, v102, v74
	v_add_f32_e32 v103, v103, v75
	v_lshlrev_b32_e32 v74, 16, v139
	v_and_b32_e32 v75, 0xffff0000, v139
	v_add_f32_e32 v104, v104, v74
	v_add_f32_e32 v105, v105, v75
	v_lshlrev_b32_e32 v74, 16, v140
	v_and_b32_e32 v75, 0xffff0000, v140
	v_add_f32_e32 v106, v106, v74
	v_add_f32_e32 v107, v107, v75
	v_lshlrev_b32_e32 v74, 16, v141
	v_and_b32_e32 v75, 0xffff0000, v141
	v_add_f32_e32 v108, v108, v74
	v_add_f32_e32 v109, v109, v75
	v_lshlrev_b32_e32 v74, 16, v142
	v_and_b32_e32 v75, 0xffff0000, v142
	v_add_f32_e32 v110, v110, v74
	v_add_f32_e32 v111, v111, v75
	v_lshlrev_b32_e32 v74, 16, v143
	v_and_b32_e32 v75, 0xffff0000, v143
	v_add_f32_e32 v112, v112, v74
	v_add_f32_e32 v113, v113, v75
	v_lshlrev_b32_e32 v74, 16, v144
	v_and_b32_e32 v75, 0xffff0000, v144
	v_add_f32_e32 v194, v194, v74
	v_add_f32_e32 v195, v195, v75
	v_lshlrev_b32_e32 v74, 16, v145
	v_and_b32_e32 v75, 0xffff0000, v145
	v_add_f32_e32 v196, v196, v74
	v_add_f32_e32 v197, v197, v75
	v_lshlrev_b32_e32 v74, 16, v146
	v_and_b32_e32 v75, 0xffff0000, v146
	v_add_f32_e32 v102, v102, v74
	v_add_f32_e32 v103, v103, v75
	v_lshlrev_b32_e32 v74, 16, v147
	v_and_b32_e32 v75, 0xffff0000, v147
	v_add_f32_e32 v104, v104, v74
	v_add_f32_e32 v105, v105, v75
	v_lshlrev_b32_e32 v74, 16, v148
	v_and_b32_e32 v75, 0xffff0000, v148
	v_add_f32_e32 v106, v106, v74
	v_add_f32_e32 v107, v107, v75
	v_lshlrev_b32_e32 v74, 16, v149
	v_and_b32_e32 v75, 0xffff0000, v149
	v_add_f32_e32 v108, v108, v74
	v_add_f32_e32 v109, v109, v75
	v_lshlrev_b32_e32 v74, 16, v150
	v_and_b32_e32 v75, 0xffff0000, v150
	v_add_f32_e32 v110, v110, v74
	v_add_f32_e32 v111, v111, v75
	v_lshlrev_b32_e32 v74, 16, v151
	v_and_b32_e32 v75, 0xffff0000, v151
	v_add_f32_e32 v112, v112, v74
	v_add_f32_e32 v113, v113, v75
	v_lshlrev_b32_e32 v74, 16, v152
	v_and_b32_e32 v75, 0xffff0000, v152
	v_add_f32_e32 v194, v194, v74
	v_add_f32_e32 v195, v195, v75
	v_lshlrev_b32_e32 v74, 16, v153
	v_and_b32_e32 v75, 0xffff0000, v153
	v_add_f32_e32 v196, v196, v74
	v_add_f32_e32 v197, v197, v75
	v_lshlrev_b32_e32 v74, 16, v154
	v_and_b32_e32 v75, 0xffff0000, v154
	v_add_f32_e32 v102, v102, v74
	v_add_f32_e32 v103, v103, v75
	v_lshlrev_b32_e32 v74, 16, v155
	v_and_b32_e32 v75, 0xffff0000, v155
	v_add_f32_e32 v104, v104, v74
	v_add_f32_e32 v105, v105, v75
	v_lshlrev_b32_e32 v74, 16, v156
	v_and_b32_e32 v75, 0xffff0000, v156
	v_add_f32_e32 v106, v106, v74
	v_add_f32_e32 v107, v107, v75
	v_lshlrev_b32_e32 v74, 16, v157
	v_and_b32_e32 v75, 0xffff0000, v157
	v_add_f32_e32 v108, v108, v74
	v_add_f32_e32 v109, v109, v75
	v_lshlrev_b32_e32 v74, 16, v158
	v_and_b32_e32 v75, 0xffff0000, v158
	v_add_f32_e32 v110, v110, v74
	v_add_f32_e32 v111, v111, v75
	v_lshlrev_b32_e32 v74, 16, v159
	v_and_b32_e32 v75, 0xffff0000, v159
	v_add_f32_e32 v112, v112, v74
	v_add_f32_e32 v113, v113, v75
	v_lshlrev_b32_e32 v74, 16, v160
	v_and_b32_e32 v75, 0xffff0000, v160
	v_add_f32_e32 v194, v194, v74
	v_add_f32_e32 v195, v195, v75
	v_lshlrev_b32_e32 v74, 16, v161
	v_and_b32_e32 v75, 0xffff0000, v161
	v_add_f32_e32 v196, v196, v74
	v_add_f32_e32 v197, v197, v75
	s_cmp_eq_u32 s13, 8
	s_cbranch_scc0 .Lctxx_sum_done
	v_lshlrev_b32_e32 v74, 16, v162
	v_and_b32_e32 v75, 0xffff0000, v162
	v_add_f32_e32 v102, v102, v74
	v_add_f32_e32 v103, v103, v75
	v_lshlrev_b32_e32 v74, 16, v163
	v_and_b32_e32 v75, 0xffff0000, v163
	v_add_f32_e32 v104, v104, v74
	v_add_f32_e32 v105, v105, v75
	v_lshlrev_b32_e32 v74, 16, v164
	v_and_b32_e32 v75, 0xffff0000, v164
	v_add_f32_e32 v106, v106, v74
	v_add_f32_e32 v107, v107, v75
	v_lshlrev_b32_e32 v74, 16, v165
	v_and_b32_e32 v75, 0xffff0000, v165
	v_add_f32_e32 v108, v108, v74
	v_add_f32_e32 v109, v109, v75
	v_lshlrev_b32_e32 v74, 16, v166
	v_and_b32_e32 v75, 0xffff0000, v166
	v_add_f32_e32 v110, v110, v74
	v_add_f32_e32 v111, v111, v75
	v_lshlrev_b32_e32 v74, 16, v167
	v_and_b32_e32 v75, 0xffff0000, v167
	v_add_f32_e32 v112, v112, v74
	v_add_f32_e32 v113, v113, v75
	v_lshlrev_b32_e32 v74, 16, v168
	v_and_b32_e32 v75, 0xffff0000, v168
	v_add_f32_e32 v194, v194, v74
	v_add_f32_e32 v195, v195, v75
	v_lshlrev_b32_e32 v74, 16, v169
	v_and_b32_e32 v75, 0xffff0000, v169
	v_add_f32_e32 v196, v196, v74
	v_add_f32_e32 v197, v197, v75
	v_lshlrev_b32_e32 v74, 16, v170
	v_and_b32_e32 v75, 0xffff0000, v170
	v_add_f32_e32 v102, v102, v74
	v_add_f32_e32 v103, v103, v75
	v_lshlrev_b32_e32 v74, 16, v171
	v_and_b32_e32 v75, 0xffff0000, v171
	v_add_f32_e32 v104, v104, v74
	v_add_f32_e32 v105, v105, v75
	v_lshlrev_b32_e32 v74, 16, v172
	v_and_b32_e32 v75, 0xffff0000, v172
	v_add_f32_e32 v106, v106, v74
	v_add_f32_e32 v107, v107, v75
	v_lshlrev_b32_e32 v74, 16, v173
	v_and_b32_e32 v75, 0xffff0000, v173
	v_add_f32_e32 v108, v108, v74
	v_add_f32_e32 v109, v109, v75
	v_lshlrev_b32_e32 v74, 16, v174
	v_and_b32_e32 v75, 0xffff0000, v174
	v_add_f32_e32 v110, v110, v74
	v_add_f32_e32 v111, v111, v75
	v_lshlrev_b32_e32 v74, 16, v175
	v_and_b32_e32 v75, 0xffff0000, v175
	v_add_f32_e32 v112, v112, v74
	v_add_f32_e32 v113, v113, v75
; __device__ __forceinline__ void ln_rows_ctx(float* xC, const float* xCin, const float* g, const float* b, const float* modp, bf16* U, int gw, int ngw, int lane, const float* part, const float* gate8, int nsplit) {
;     ...
;             if (part) { const bf16* pp = (const bf16*)part + (size_t)r * DM + col; f32x4 ps = {0.f, 0.f, 0.f, 0.f};
;                 for (int k = 0; k < nsplit; ++k) { const v2u w = *(const v2u*)(pp + (size_t)k * 2048 * 1024); ps = ps + (f32x4){bflo(w.x), bfhi(w.x), bflo(w.y), bfhi(w.y)}; }
	v_lshlrev_b32_e32 v74, 16, v176
	v_and_b32_e32 v75, 0xffff0000, v176
	v_add_f32_e32 v194, v194, v74
	v_add_f32_e32 v195, v195, v75
	v_lshlrev_b32_e32 v74, 16, v177
	v_and_b32_e32 v75, 0xffff0000, v177
	v_add_f32_e32 v196, v196, v74
	v_add_f32_e32 v197, v197, v75
	v_lshlrev_b32_e32 v74, 16, v178
	v_and_b32_e32 v75, 0xffff0000, v178
	v_add_f32_e32 v102, v102, v74
	v_add_f32_e32 v103, v103, v75
	v_lshlrev_b32_e32 v74, 16, v179
	v_and_b32_e32 v75, 0xffff0000, v179
	v_add_f32_e32 v104, v104, v74
	v_add_f32_e32 v105, v105, v75
	v_lshlrev_b32_e32 v74, 16, v180
	v_and_b32_e32 v75, 0xffff0000, v180
	v_add_f32_e32 v106, v106, v74
	v_add_f32_e32 v107, v107, v75
	v_lshlrev_b32_e32 v74, 16, v181
	v_and_b32_e32 v75, 0xffff0000, v181
	v_add_f32_e32 v108, v108, v74
	v_add_f32_e32 v109, v109, v75
	v_lshlrev_b32_e32 v74, 16, v182
	v_and_b32_e32 v75, 0xffff0000, v182
	v_add_f32_e32 v110, v110, v74
	v_add_f32_e32 v111, v111, v75
	v_lshlrev_b32_e32 v74, 16, v183
	v_and_b32_e32 v75, 0xffff0000, v183
	v_add_f32_e32 v112, v112, v74
	v_add_f32_e32 v113, v113, v75
	v_lshlrev_b32_e32 v74, 16, v184
	v_and_b32_e32 v75, 0xffff0000, v184
	v_add_f32_e32 v194, v194, v74
	v_add_f32_e32 v195, v195, v75
	v_lshlrev_b32_e32 v74, 16, v185
	v_and_b32_e32 v75, 0xffff0000, v185
	v_add_f32_e32 v196, v196, v74
	v_add_f32_e32 v197, v197, v75
	v_lshlrev_b32_e32 v74, 16, v186
	v_and_b32_e32 v75, 0xffff0000, v186
	v_add_f32_e32 v102, v102, v74
	v_add_f32_e32 v103, v103, v75
	v_lshlrev_b32_e32 v74, 16, v187
	v_and_b32_e32 v75, 0xffff0000, v187
	v_add_f32_e32 v104, v104, v74
	v_add_f32_e32 v105, v105, v75
	v_lshlrev_b32_e32 v74, 16, v188
	v_and_b32_e32 v75, 0xffff0000, v188
	v_add_f32_e32 v106, v106, v74
	v_add_f32_e32 v107, v107, v75
	v_lshlrev_b32_e32 v74, 16, v189
	v_and_b32_e32 v75, 0xffff0000, v189
	v_add_f32_e32 v108, v108, v74
	v_add_f32_e32 v109, v109, v75
	v_lshlrev_b32_e32 v74, 16, v190
	v_and_b32_e32 v75, 0xffff0000, v190
	v_add_f32_e32 v110, v110, v74
	v_add_f32_e32 v111, v111, v75
	v_lshlrev_b32_e32 v74, 16, v191
	v_and_b32_e32 v75, 0xffff0000, v191
	v_add_f32_e32 v112, v112, v74
	v_add_f32_e32 v113, v113, v75
	v_lshlrev_b32_e32 v74, 16, v192
	v_and_b32_e32 v75, 0xffff0000, v192
	v_add_f32_e32 v194, v194, v74
	v_add_f32_e32 v195, v195, v75
	v_lshlrev_b32_e32 v74, 16, v193
	v_and_b32_e32 v75, 0xffff0000, v193
	v_add_f32_e32 v196, v196, v74
	v_add_f32_e32 v197, v197, v75
; __device__ __forceinline__ unsigned pk2(float lo, float hi) { return f2bf(lo) | (f2bf(hi) << 16); }
; __device__ __forceinline__ void ln_rows_ctx(float* xC, const float* xCin, const float* g, const float* b, const float* modp, bf16* U, int gw, int ngw, int lane, const float* part, const float* gate8, int nsplit) {
;     ...
;                 v[j] = v[j] * ALPHA + *(const f32x4*)(gate8 + col) * ps; }
;             s += (v[j][0] + v[j][1]) + (v[j][2] + v[j][3]); }
;         const float mean = wave_sum(s) * (1.0f / DM); float s2 = 0.f;
; #pragma unroll
;         for (int j = 0; j < 4; ++j) { v[j] = v[j] - mean; s2 += (v[j][0] * v[j][0] + v[j][1] * v[j][1]) + (v[j][2] * v[j][2] + v[j][3] * v[j][3]); }
;         const float rstd = rsqrtf(wave_sum(s2) * (1.0f / DM) + EPSN);
; #pragma unroll
;         for (int j = 0; j < 4; ++j) { const int col = 4 * (lane + 64 * j); const f32x4 o = v[j] * rstd * *(const f32x4*)(g + col) + *(const f32x4*)(b + col);
;             *(f32x4*)(xC + (size_t)r * DM + col) = o;
;             if (modp) { const float* mp = modp + (size_t)8 * 6144; const f32x4 sh = *(const f32x4*)(mp + col), sc = *(const f32x4*)(mp + 1024 + col); const f32x4 uu = o * (sc + 1.0f) + sh;
;                 v2u w; w.x = pk2(uu[0], uu[1]); w.y = pk2(uu[2], uu[3]); *(v2u*)(U + (size_t)(ML + r) * DM + col) = w; } }
.Lctxx_sum_done:
	v_mul_f32_e32 v102, v24, v102
	v_mul_f32_e32 v103, v25, v103
	v_mul_f32_e32 v104, v26, v104
	v_mul_f32_e32 v105, v27, v105
	v_mul_f32_e32 v106, v28, v106
	v_mul_f32_e32 v107, v29, v107
	v_mul_f32_e32 v108, v30, v108
	v_mul_f32_e32 v109, v31, v109
	v_mul_f32_e32 v110, v32, v110
	v_mul_f32_e32 v111, v33, v111
	v_mul_f32_e32 v112, v34, v112
	v_mul_f32_e32 v113, v35, v113
	v_mul_f32_e32 v194, v36, v194
	v_mul_f32_e32 v195, v37, v195
	v_mul_f32_e32 v196, v38, v196
	v_mul_f32_e32 v197, v39, v197
	v_fma_f32 v8, v8, s86, v102
	v_fma_f32 v9, v9, s86, v103
	v_fma_f32 v10, v10, s86, v104
	v_fma_f32 v11, v11, s86, v105
	v_fma_f32 v12, v12, s86, v106
	v_fma_f32 v13, v13, s86, v107
	v_fma_f32 v14, v14, s86, v108
	v_fma_f32 v15, v15, s86, v109
	v_fma_f32 v16, v16, s86, v110
	v_fma_f32 v17, v17, s86, v111
	v_fma_f32 v18, v18, s86, v112
	v_fma_f32 v19, v19, s86, v113
	v_fma_f32 v20, v20, s86, v194
	v_fma_f32 v21, v21, s86, v195
	v_fma_f32 v22, v22, s86, v196
	v_fma_f32 v23, v23, s86, v197
	v_add_f32_e32 v76, v8, v9
	v_add_f32_e32 v77, v10, v11
	v_add_f32_e32 v76, v76, v12
	v_add_f32_e32 v77, v77, v13
	v_add_f32_e32 v76, v76, v14
	v_add_f32_e32 v77, v77, v15
	v_add_f32_e32 v76, v76, v16
	v_add_f32_e32 v77, v77, v17
	v_add_f32_e32 v76, v76, v18
	v_add_f32_e32 v77, v77, v19
	v_add_f32_e32 v76, v76, v20
	v_add_f32_e32 v77, v77, v21
	v_add_f32_e32 v76, v76, v22
	v_add_f32_e32 v77, v77, v23
	v_add_f32_e32 v76, v76, v77
	ds_swizzle_b32 v72, v76 offset:0x041f
	s_waitcnt lgkmcnt(0)
	v_add_f32_e32 v76, v76, v72
	ds_swizzle_b32 v72, v76 offset:0x081f
	s_waitcnt lgkmcnt(0)
	v_add_f32_e32 v76, v76, v72
	ds_swizzle_b32 v72, v76 offset:0x101f
	s_waitcnt lgkmcnt(0)
	v_add_f32_e32 v76, v76, v72
	ds_swizzle_b32 v72, v76 offset:0x201f
	s_waitcnt lgkmcnt(0)
	v_add_f32_e32 v76, v76, v72
	ds_swizzle_b32 v72, v76 offset:0x401f
	s_waitcnt lgkmcnt(0)
	v_add_f32_e32 v76, v76, v72
	v_mov_b32_e32 v72, v76
	s_nop 1
	v_permlane32_swap_b32_e32 v76, v72
	v_add_f32_e32 v76, v76, v72
	v_mul_f32_e32 v76, 0x3a800000, v76
	v_sub_f32_e32 v8, v8, v76
	v_sub_f32_e32 v9, v9, v76
	v_sub_f32_e32 v10, v10, v76
	v_sub_f32_e32 v11, v11, v76
	v_sub_f32_e32 v12, v12, v76
	v_sub_f32_e32 v13, v13, v76
	v_sub_f32_e32 v14, v14, v76
	v_sub_f32_e32 v15, v15, v76
	v_sub_f32_e32 v16, v16, v76
	v_sub_f32_e32 v17, v17, v76
	v_sub_f32_e32 v18, v18, v76
	v_sub_f32_e32 v19, v19, v76
	v_sub_f32_e32 v20, v20, v76
	v_sub_f32_e32 v21, v21, v76
	v_sub_f32_e32 v22, v22, v76
	v_sub_f32_e32 v23, v23, v76
	v_mul_f32_e32 v76, v8, v8
	v_mul_f32_e32 v77, v9, v9
	v_fmac_f32_e32 v76, v10, v10
	v_fmac_f32_e32 v77, v11, v11
	v_fmac_f32_e32 v76, v12, v12
	v_fmac_f32_e32 v77, v13, v13
	v_fmac_f32_e32 v76, v14, v14
	v_fmac_f32_e32 v77, v15, v15
	v_fmac_f32_e32 v76, v16, v16
	v_fmac_f32_e32 v77, v17, v17
	v_fmac_f32_e32 v76, v18, v18
	v_fmac_f32_e32 v77, v19, v19
	v_fmac_f32_e32 v76, v20, v20
	v_fmac_f32_e32 v77, v21, v21
	v_fmac_f32_e32 v76, v22, v22
	v_fmac_f32_e32 v77, v23, v23
	v_add_f32_e32 v76, v76, v77
	ds_swizzle_b32 v72, v76 offset:0x041f
	s_waitcnt lgkmcnt(0)
	v_add_f32_e32 v76, v76, v72
	ds_swizzle_b32 v72, v76 offset:0x081f
	s_waitcnt lgkmcnt(0)
	v_add_f32_e32 v76, v76, v72
	ds_swizzle_b32 v72, v76 offset:0x101f
	s_waitcnt lgkmcnt(0)
	v_add_f32_e32 v76, v76, v72
	ds_swizzle_b32 v72, v76 offset:0x201f
	s_waitcnt lgkmcnt(0)
	v_add_f32_e32 v76, v76, v72
	ds_swizzle_b32 v72, v76 offset:0x401f
	s_waitcnt lgkmcnt(0)
	v_add_f32_e32 v76, v76, v72
	v_mov_b32_e32 v72, v76
	s_nop 1
	v_permlane32_swap_b32_e32 v76, v72
	v_add_f32_e32 v76, v76, v72
	v_mov_b32_e32 v78, 0x3a800000
	v_mov_b32_e32 v79, 0x358637bd
	v_fma_f32 v76, v76, v78, v79
	v_rsq_f32_e32 v76, v76
	s_nop 0
	v_mul_f32_e32 v8, v8, v76
	v_mul_f32_e32 v9, v9, v76
	v_mul_f32_e32 v10, v10, v76
	v_mul_f32_e32 v11, v11, v76
	v_mul_f32_e32 v12, v12, v76
	v_mul_f32_e32 v13, v13, v76
	v_mul_f32_e32 v14, v14, v76
	v_mul_f32_e32 v15, v15, v76
	v_mul_f32_e32 v16, v16, v76
	v_mul_f32_e32 v17, v17, v76
	v_mul_f32_e32 v18, v18, v76
	v_mul_f32_e32 v19, v19, v76
	v_mul_f32_e32 v20, v20, v76
	v_mul_f32_e32 v21, v21, v76
	v_mul_f32_e32 v22, v22, v76
	v_mul_f32_e32 v23, v23, v76
	v_fma_f32 v8, v8, v40, v56
	v_fma_f32 v9, v9, v41, v57
	v_fma_f32 v10, v10, v42, v58
	v_fma_f32 v11, v11, v43, v59
	v_fma_f32 v12, v12, v44, v60
	v_fma_f32 v13, v13, v45, v61
	v_fma_f32 v14, v14, v46, v62
	v_fma_f32 v15, v15, v47, v63
	v_fma_f32 v16, v16, v48, v64
	v_fma_f32 v17, v17, v49, v65
	v_fma_f32 v18, v18, v50, v66
	v_fma_f32 v19, v19, v51, v67
	v_fma_f32 v20, v20, v52, v68
	v_fma_f32 v21, v21, v53, v69
	v_fma_f32 v22, v22, v54, v70
	v_fma_f32 v23, v23, v55, v71
	global_store_dwordx4 v3, v[8:11], s[24:25]
	global_store_dwordx4 v3, v[12:15], s[24:25] offset:1024
	global_store_dwordx4 v3, v[16:19], s[24:25] offset:2048
	global_store_dwordx4 v3, v[20:23], s[24:25] offset:3072
	v_add_f32_e32 v226, 1.0, v226
	v_add_f32_e32 v227, 1.0, v227
	v_add_f32_e32 v228, 1.0, v228
	v_add_f32_e32 v229, 1.0, v229
	v_add_f32_e32 v230, 1.0, v230
	v_add_f32_e32 v231, 1.0, v231
	v_add_f32_e32 v232, 1.0, v232
	v_add_f32_e32 v233, 1.0, v233
	v_add_f32_e32 v234, 1.0, v234
	v_add_f32_e32 v235, 1.0, v235
	v_add_f32_e32 v236, 1.0, v236
	v_add_f32_e32 v237, 1.0, v237
	v_add_f32_e32 v238, 1.0, v238
	v_add_f32_e32 v239, 1.0, v239
	v_add_f32_e32 v240, 1.0, v240
	v_add_f32_e32 v241, 1.0, v241
	v_fma_f32 v102, v8, v226, v86
	v_fma_f32 v103, v9, v227, v87
	v_fma_f32 v104, v10, v228, v88
	v_fma_f32 v105, v11, v229, v89
	v_fma_f32 v106, v12, v230, v90
	v_fma_f32 v107, v13, v231, v91
	v_fma_f32 v108, v14, v232, v92
	v_fma_f32 v109, v15, v233, v93
	v_fma_f32 v110, v16, v234, v94
	v_fma_f32 v111, v17, v235, v95
	v_fma_f32 v112, v18, v236, v96
	v_fma_f32 v113, v19, v237, v97
	v_fma_f32 v194, v20, v238, v98
	v_fma_f32 v195, v21, v239, v99
	v_fma_f32 v196, v22, v240, v100
	v_fma_f32 v197, v23, v241, v101
	v_cvt_pk_bf16_f32 v242, v102, v103
	v_cvt_pk_bf16_f32 v243, v104, v105
	global_store_dwordx2 v4, v[242:243], s[22:23]
	v_cvt_pk_bf16_f32 v244, v106, v107
	v_cvt_pk_bf16_f32 v245, v108, v109
	global_store_dwordx2 v4, v[244:245], s[22:23] offset:512
	v_cvt_pk_bf16_f32 v246, v110, v111
	v_cvt_pk_bf16_f32 v247, v112, v113
	global_store_dwordx2 v4, v[246:247], s[22:23] offset:1024
	v_cvt_pk_bf16_f32 v248, v194, v195
	v_cvt_pk_bf16_f32 v249, v196, v197
	global_store_dwordx2 v4, v[248:249], s[22:23] offset:1536
	s_cmp_eq_u32 s19, 0
	s_cbranch_scc1 .Lctxx_ret0
	s_branch .Lctxx_ret1
.Lctxx_ret0:
	v_readlane_b32 s4, v255, 3
	v_readlane_b32 s5, v255, 4
	v_readlane_b32 s6, v254, 33
	v_readlane_b32 s12, v252, 47

; __device__ __forceinline__ unsigned pk2(float lo, float hi) { return f2bf(lo) | (f2bf(hi) << 16); }
; #define IDS() int tid_ = threadIdx.x; asm volatile("" : "+v"(tid_)); const int lane_ = tid_ & 63, wave_ = __builtin_amdgcn_readfirstlane(tid_ >> 6); const int gw_ = vcu * NWAVES + wave_; (void)lane_; (void)gw_
; __device__ __forceinline__ void ln_rows_ctx(float* xC, const float* xCin, const float* g, const float* b, const float* modp, bf16* U, int gw, int ngw, int lane, const float* part, const float* gate8, int nsplit) {
;     for (int r = gw; r < MC; r += ngw) {
;         f32x4 v[4]; float s = 0.f;
; #pragma unroll
;         for (int j = 0; j < 4; ++j) { const int col = 4 * (lane + 64 * j); v[j] = *(const f32x4*)(xCin + (size_t)r * DM + col);
;             if (part) { const bf16* pp = (const bf16*)part + (size_t)r * DM + col; f32x4 ps = {0.f, 0.f, 0.f, 0.f};
;                 for (int k = 0; k < nsplit; ++k) { const v2u w = *(const v2u*)(pp + (size_t)k * 2048 * 1024); ps = ps + (f32x4){bflo(w.x), bfhi(w.x), bflo(w.y), bfhi(w.y)}; }
;                 v[j] = v[j] * ALPHA + *(const f32x4*)(gate8 + col) * ps; }
;             s += (v[j][0] + v[j][1]) + (v[j][2] + v[j][3]); }
;         const float mean = wave_sum(s) * (1.0f / DM); float s2 = 0.f;
; #pragma unroll
;         for (int j = 0; j < 4; ++j) { v[j] = v[j] - mean; s2 += (v[j][0] * v[j][0] + v[j][1] * v[j][1]) + (v[j][2] * v[j][2] + v[j][3] * v[j][3]); }
;         const float rstd = rsqrtf(wave_sum(s2) * (1.0f / DM) + EPSN);
; #pragma unroll
;         for (int j = 0; j < 4; ++j) { const int col = 4 * (lane + 64 * j); const f32x4 o = v[j] * rstd * *(const f32x4*)(g + col) + *(const f32x4*)(b + col);
;             *(f32x4*)(xC + (size_t)r * DM + col) = o;
;             if (modp) { const float* mp = modp + (size_t)8 * 6144; const f32x4 sh = *(const f32x4*)(mp + col), sc = *(const f32x4*)(mp + 1024 + col); const f32x4 uu = o * (sc + 1.0f) + sh;
;                 v2u w; w.x = pk2(uu[0], uu[1]); w.y = pk2(uu[2], uu[3]); *(v2u*)(U + (size_t)(ML + r) * DM + col) = w; } }
;     }
; __global__ void __launch_bounds__(NTHR, 2) trunk_fwd(Args a) {
;     ...
;         { IDS(); ln_rows(a.out, XC, mrows, a.ln2_g + l * DM, a.ln2_b + l * DM, need_ctx ? modl + 9 * 6144 : nullptr, U, gw_, ngw, lane_, nullptr, need_ctx ? RETC : nullptr, modl + 5 * 1024 + 8 * 6144, nullptr, U, need_ctx ? (bf16*)a.out : nullptr, 8); }
.LBB0_1836:
	s_cmpk_gt_i32 s38, 0x7ff
	v_readlane_b32 s2, v253, 43
	s_cselect_b64 s[0:1], -1, 0
	v_readlane_b32 s3, v253, 44
	s_or_b64 s[0:1], s[2:3], s[0:1]
	s_and_b64 vcc, exec, s[0:1]
	s_movk_i32 s16, 0x1100
	s_movk_i32 s17, 0xff
	s_mov_b32 s18, 0x3e000000
	s_cbranch_vccnz .LBB0_1839
	v_readlane_b32 s26, v253, 41
	s_mov_b32 s7, s38
	s_mov_b64 s[14:15], s[10:11]
	s_mov_b64 s[10:11], s[8:9]
	s_nop 1
	s_mul_i32 s27, s26, 0x36000
	s_add_u32 s28, s94, 0x5a00000
	s_addc_u32 s29, s95, 0
	s_add_u32 s28, s28, s27
	s_addc_u32 s29, s29, 0
	s_add_u32 s8, s28, 0x35000
	s_addc_u32 s9, s29, 0
	s_add_u32 s20, s28, 0x66000
	s_addc_u32 s21, s29, 0
	s_add_u32 s2, s94, 0x6800000
	s_addc_u32 s3, s95, 0
	s_add_u32 s24, s94, 0x6000000
	s_addc_u32 s25, s95, 0
	s_add_u32 s22, s64, 0x4000000
	s_addc_u32 s23, s65, 0
	s_mov_b64 s[0:1], s[24:25]
	s_mov_b32 s13, 8
	s_mov_b32 s19, 1
	s_branch .Lctxx_entry
.Lctxx_ret1:
.LBB0_1839:
	s_and_b64 vcc, exec, s[82:83]
	s_mov_b32 s35, 0xbfb8aa3b
	s_mov_b32 s37, 0xb2a5705f
	s_mov_b32 s38, 0x42ce8ed0
	s_mov_b32 s39, 0xc2b17218
	s_mov_b32 s46, 0x7f800000
	s_mov_b32 s54, 0x40000
	s_mov_b32 s55, 0x48000
	s_mov_b32 s59, 0x50000
	s_mov_b32 s61, 0x58000
	s_mov_b64 s[70:71], 0x10000
	v_readlane_b32 s26, v253, 41
	v_readlane_b32 s27, v253, 42
	s_cbranch_vccz .LBB0_1840
	s_getpc_b64 s[98:99]
